# v66 plus epilogue code prefetch: at the first instruction of the P6 and P9 LayerNorm epilogues every thread reads a 128-byte slice of the upcoming code (clamped inside the kernel, dumped in spare v243
# speedup vs baseline: 1.0138x; 1.0041x over previous
.LBB0_456:
	s_getpc_b64 s[98:99]
	v_lshlrev_b32_e32 v243, 7, v215
	v_min_u32_e32 v243, 0x5780, v243
	global_load_dword v243, v243, s[98:99]
	s_add_i32 s1, s86, -16
	s_lshr_b32 s1, s1, 3
	s_mulk_i32 s1, 0x1800
	s_lshl_b32 s0, s35, 5
	s_addk_i32 s1, 0x1800
	s_cmp_gt_i32 s86, 15
	s_cselect_b32 s6, s1, 0
	s_lshl_b32 s1, s2, 8
	v_lshrrev_b32_e32 v130, 1, v215
	s_mov_b32 s7, 0
	s_or_b32 s0, s1, s0
	v_and_or_b32 v210, v130, 24, s0
	s_lshl_b64 s[0:1], s[6:7], 2
	v_readlane_b32 s4, v242, 34
	v_readlane_b32 s5, v242, 35
	s_add_u32 s28, s4, s0
	s_addc_u32 s29, s5, s1
	s_lshl_b32 s26, s86, 8
	s_add_i32 s0, s26, s36
	v_or_b32_e32 v218, s0, v150
	s_movk_i32 s0, 0x1000
	v_ashrrev_i32_e32 v211, 31, v210
	v_add_u32_e32 v130, 0xfffff000, v218
	v_ashrrev_i32_e32 v131, 31, v218
	v_cmp_gt_i32_e32 vcc, s0, v218
	v_lshlrev_b64 v[212:213], 2, v[210:211]
	v_mov_b32_e32 v219, s59
	v_cndmask_b32_e32 v131, 0, v131, vcc
	v_cndmask_b32_e32 v130, v130, v218, vcc
	v_mov_b32_e32 v220, s57
	v_mov_b32_e32 v221, s58
	v_mov_b32_e32 v222, s56
	v_lshl_add_u64 v[146:147], s[28:29], 0, v[212:213]
	v_cndmask_b32_e32 v133, v219, v220, vcc
	v_cndmask_b32_e32 v132, v221, v222, vcc
	v_lshlrev_b64 v[130:131], 12, v[130:131]
	s_movk_i32 s1, 0x2000
	s_mov_b64 s[4:5], 0x2000
	v_lshl_add_u64 v[130:131], v[132:133], 0, v[130:131]
	v_add_co_u32_e32 v148, vcc, s1, v146
	v_lshl_add_u64 v[142:143], v[130:131], 0, v[212:213]
	s_nop 0
	v_addc_co_u32_e32 v149, vcc, 0, v147, vcc
	v_lshl_add_u64 v[146:147], v[146:147], 0, s[4:5]
	s_barrier
	global_load_dwordx4 v[130:133], v[142:143], off offset:16
	global_load_dwordx4 v[134:137], v[142:143], off
	global_load_dwordx4 v[138:141], v[142:143], off offset:528
	s_nop 0
	global_load_dwordx4 v[142:145], v[142:143], off offset:512
	v_and_b32_e32 v217, 63, v215
	global_load_dwordx4 v[178:181], v[148:149], off
	global_load_dwordx4 v[174:177], v[146:147], off offset:16
	global_load_dwordx4 v[170:173], v[146:147], off offset:512
	global_load_dwordx4 v[166:169], v[146:147], off offset:528
	v_or_b32_e32 v146, 16, v218
	v_add_u32_e32 v148, 0xfffff010, v218
	v_ashrrev_i32_e32 v147, 31, v146
	v_cmp_gt_i32_e32 vcc, s0, v146
	s_mov_b32 s6, 0x3f9837f0
	v_readlane_b32 s8, v242, 16
	v_cndmask_b32_e32 v147, 0, v147, vcc
	v_cndmask_b32_e32 v146, v148, v146, vcc
	v_cndmask_b32_e32 v149, v219, v220, vcc
	v_cndmask_b32_e32 v148, v221, v222, vcc
	v_lshlrev_b64 v[146:147], 12, v[146:147]
	v_lshl_add_u64 v[146:147], v[148:149], 0, v[146:147]
	v_lshl_add_u64 v[146:147], v[146:147], 0, v[212:213]
	global_load_dwordx4 v[224:227], v[146:147], off
	global_load_dwordx4 v[228:231], v[146:147], off offset:16
	global_load_dwordx4 v[232:235], v[146:147], off offset:512
	global_load_dwordx4 v[236:239], v[146:147], off offset:528
	v_or_b32_e32 v223, 32, v218
	v_lshlrev_b32_e32 v146, 6, v217
	v_readlane_b32 s20, v242, 28
	v_readlane_b32 s21, v242, 29
	v_add_u32_e32 v240, 0xfffff020, v218
	v_ashrrev_i32_e32 v241, 31, v223
	v_cmp_gt_i32_e32 vcc, s0, v223
	v_readlane_b32 s22, v242, 30
	v_readlane_b32 s23, v242, 31
	global_load_dwordx4 v[162:165], v146, s[20:21] offset:48
	s_nop 3
	global_load_dwordx4 v[182:185], v146, s[22:23] offset:48
	global_load_dwordx4 v[186:189], v146, s[20:21] offset:32
	global_load_dwordx4 v[190:193], v146, s[22:23] offset:32
	global_load_dwordx4 v[194:197], v146, s[20:21] offset:16
	global_load_dwordx4 v[198:201], v146, s[22:23] offset:16
	global_load_dwordx4 v[202:205], v146, s[20:21]
	global_load_dwordx4 v[206:209], v146, s[22:23]
	v_readlane_b32 s9, v242, 17
	v_readlane_b32 s10, v242, 18
	v_readlane_b32 s11, v242, 19
	v_readlane_b32 s12, v242, 20
	v_readlane_b32 s13, v242, 21
	v_readlane_b32 s14, v242, 22
	v_readlane_b32 s15, v242, 23
	v_readlane_b32 s16, v242, 24
	v_readlane_b32 s17, v242, 25
	v_readlane_b32 s18, v242, 26
	v_readlane_b32 s19, v242, 27
	s_waitcnt vmcnt(0)
	v_pk_mul_f32 v[130:131], v[130:131], s[6:7] op_sel_hi:[1,0]
	v_pk_mul_f32 v[138:139], v[138:139], s[6:7] op_sel_hi:[1,0]
	v_pk_mul_f32 v[140:141], v[140:141], s[6:7] op_sel_hi:[1,0]
	v_pk_mul_f32 v[136:137], v[136:137], s[6:7] op_sel_hi:[1,0]
	v_pk_mul_f32 v[134:135], v[134:135], s[6:7] op_sel_hi:[1,0]
	v_pk_fma_f32 v[146:147], v[106:107], v[166:167], v[138:139]
	v_cndmask_b32_e32 v107, 0, v241, vcc
	v_cndmask_b32_e32 v106, v240, v223, vcc
	v_pk_fma_f32 v[148:149], v[108:109], v[168:169], v[140:141]
	v_cndmask_b32_e32 v109, v219, v220, vcc
	v_cndmask_b32_e32 v108, v221, v222, vcc
	v_lshlrev_b64 v[106:107], 12, v[106:107]
	v_pk_mul_f32 v[132:133], v[132:133], s[6:7] op_sel_hi:[1,0]
	v_pk_mul_f32 v[144:145], v[144:145], s[6:7] op_sel_hi:[1,0]
	v_pk_mul_f32 v[142:143], v[142:143], s[6:7] op_sel_hi:[1,0]
	v_pk_fma_f32 v[154:155], v[122:123], v[174:175], v[130:131]
	v_lshl_add_u64 v[106:107], v[108:109], 0, v[106:107]
	v_pk_mul_f32 v[130:131], v[226:227], s[6:7] op_sel_hi:[1,0]
	v_pk_fma_f32 v[160:161], v[128:129], v[180:181], v[136:137]
	v_pk_fma_f32 v[158:159], v[126:127], v[178:179], v[134:135]
	v_pk_fma_f32 v[156:157], v[124:125], v[176:177], v[132:133]
	v_pk_fma_f32 v[152:153], v[112:113], v[172:173], v[144:145]
	v_pk_fma_f32 v[150:151], v[110:111], v[170:171], v[142:143]
	v_lshl_add_u64 v[126:127], v[106:107], 0, v[212:213]
	v_pk_mul_f32 v[132:133], v[224:225], s[6:7] op_sel_hi:[1,0]
	v_pk_fma_f32 v[144:145], v[120:121], v[180:181], v[130:131]
	v_pk_mul_f32 v[120:121], v[228:229], s[6:7] op_sel_hi:[1,0]
	global_load_dwordx4 v[106:109], v[126:127], off
	global_load_dwordx4 v[110:113], v[126:127], off offset:16
	global_load_dwordx4 v[122:125], v[126:127], off offset:528
	s_nop 0
	global_load_dwordx4 v[126:129], v[126:127], off offset:512
	v_pk_fma_f32 v[142:143], v[118:119], v[178:179], v[132:133]
	v_pk_mul_f32 v[118:119], v[230:231], s[6:7] op_sel_hi:[1,0]
	v_pk_fma_f32 v[138:139], v[114:115], v[174:175], v[120:121]
	v_pk_mul_f32 v[114:115], v[234:235], s[6:7] op_sel_hi:[1,0]
	v_pk_fma_f32 v[140:141], v[116:117], v[176:177], v[118:119]
	v_pk_mul_f32 v[116:117], v[232:233], s[6:7] op_sel_hi:[1,0]
	v_pk_fma_f32 v[136:137], v[104:105], v[172:173], v[114:115]
	v_pk_mul_f32 v[104:105], v[236:237], s[6:7] op_sel_hi:[1,0]
	v_pk_fma_f32 v[134:135], v[102:103], v[170:171], v[116:117]
	v_pk_mul_f32 v[102:103], v[238:239], s[6:7] op_sel_hi:[1,0]
	v_pk_fma_f32 v[130:131], v[98:99], v[166:167], v[104:105]
	v_or_b32_e32 v98, 48, v218
	v_pk_fma_f32 v[132:133], v[100:101], v[168:169], v[102:103]
	v_ashrrev_i32_e32 v99, 31, v98
	v_add_u32_e32 v100, 0xfffff030, v218
	v_cmp_gt_i32_e32 vcc, s0, v98
	v_add_u32_e32 v116, 0xfffff080, v218
	v_mul_f32_e32 v223, v202, v202
	v_cndmask_b32_e32 v99, 0, v99, vcc
	v_cndmask_b32_e32 v98, v100, v98, vcc
	v_cndmask_b32_e32 v101, v219, v220, vcc
	v_cndmask_b32_e32 v100, v221, v222, vcc
	v_lshlrev_b64 v[98:99], 12, v[98:99]
	v_lshl_add_u64 v[98:99], v[100:101], 0, v[98:99]
	v_lshl_add_u64 v[114:115], v[98:99], 0, v[212:213]
	global_load_dwordx4 v[98:101], v[114:115], off
	global_load_dwordx4 v[102:105], v[114:115], off offset:16
	global_load_dwordx4 v[224:227], v[114:115], off offset:512
	global_load_dwordx4 v[228:231], v[114:115], off offset:528
	v_add_u32_e32 v114, 0x80, v218
	v_ashrrev_i32_e32 v115, 31, v114
	v_cmp_gt_i32_e32 vcc, s0, v114
	v_fmac_f32_e32 v223, v203, v203
	v_fmac_f32_e32 v223, v204, v204
	v_cndmask_b32_e32 v115, 0, v115, vcc
	v_cndmask_b32_e32 v114, v116, v114, vcc
	v_cndmask_b32_e32 v117, v219, v220, vcc
	v_cndmask_b32_e32 v116, v221, v222, vcc
	v_lshlrev_b64 v[114:115], 12, v[114:115]
	v_lshl_add_u64 v[114:115], v[116:117], 0, v[114:115]
	v_lshl_add_u64 v[232:233], v[114:115], 0, v[212:213]
	v_fmac_f32_e32 v223, v205, v205
	v_fmac_f32_e32 v223, v194, v194
	v_fmac_f32_e32 v223, v195, v195
	v_fmac_f32_e32 v223, v196, v196
	v_fmac_f32_e32 v223, v197, v197
	v_fmac_f32_e32 v223, v186, v186
	v_fmac_f32_e32 v223, v187, v187
	v_fmac_f32_e32 v223, v188, v188
	v_fmac_f32_e32 v223, v189, v189
	v_fmac_f32_e32 v223, v162, v162
	v_fmac_f32_e32 v223, v163, v163
	v_fmac_f32_e32 v223, v164, v164
	v_fmac_f32_e32 v223, v165, v165
	s_waitcnt vmcnt(7)
	v_pk_mul_f32 v[108:109], v[108:109], s[6:7] op_sel_hi:[1,0]
	v_pk_mul_f32 v[106:107], v[106:107], s[6:7] op_sel_hi:[1,0]
	s_waitcnt vmcnt(6)
	v_pk_mul_f32 v[112:113], v[112:113], s[6:7] op_sel_hi:[1,0]
	v_pk_mul_f32 v[110:111], v[110:111], s[6:7] op_sel_hi:[1,0]
	s_waitcnt vmcnt(4)
	v_pk_mul_f32 v[114:115], v[128:129], s[6:7] op_sel_hi:[1,0]
	v_pk_mul_f32 v[116:117], v[126:127], s[6:7] op_sel_hi:[1,0]
	v_pk_mul_f32 v[234:235], v[124:125], s[6:7] op_sel_hi:[1,0]
	v_pk_mul_f32 v[236:237], v[122:123], s[6:7] op_sel_hi:[1,0]
	v_pk_fma_f32 v[128:129], v[96:97], v[180:181], v[108:109]
	v_pk_fma_f32 v[126:127], v[94:95], v[178:179], v[106:107]
	v_pk_fma_f32 v[124:125], v[92:93], v[176:177], v[112:113]
	v_pk_fma_f32 v[122:123], v[90:91], v[174:175], v[110:111]
	v_pk_fma_f32 v[120:121], v[88:89], v[172:173], v[114:115]
	v_pk_fma_f32 v[118:119], v[86:87], v[170:171], v[116:117]
	v_pk_fma_f32 v[116:117], v[84:85], v[168:169], v[234:235]
	v_pk_fma_f32 v[114:115], v[82:83], v[166:167], v[236:237]
	v_add_u32_e32 v106, 0x90, v218
	global_load_dwordx4 v[82:85], v[232:233], off
	global_load_dwordx4 v[86:89], v[232:233], off offset:16
	global_load_dwordx4 v[90:93], v[232:233], off offset:528
	global_load_dwordx4 v[94:97], v[232:233], off offset:512
	v_add_u32_e32 v108, 0xfffff090, v218
	v_ashrrev_i32_e32 v107, 31, v106
	v_cmp_gt_i32_e32 vcc, s0, v106
	s_waitcnt vmcnt(7)
	v_pk_mul_f32 v[100:101], v[100:101], s[6:7] op_sel_hi:[1,0]
	v_cndmask_b32_e32 v107, 0, v107, vcc
	v_cndmask_b32_e32 v106, v108, v106, vcc
	v_cndmask_b32_e32 v109, v219, v220, vcc
	v_cndmask_b32_e32 v108, v221, v222, vcc
	v_lshlrev_b64 v[106:107], 12, v[106:107]
	v_lshl_add_u64 v[106:107], v[108:109], 0, v[106:107]
	v_pk_mul_f32 v[98:99], v[98:99], s[6:7] op_sel_hi:[1,0]
	s_waitcnt vmcnt(6)
	v_pk_mul_f32 v[104:105], v[104:105], s[6:7] op_sel_hi:[1,0]
	v_pk_mul_f32 v[102:103], v[102:103], s[6:7] op_sel_hi:[1,0]
	s_waitcnt vmcnt(5)
	v_pk_mul_f32 v[226:227], v[226:227], s[6:7] op_sel_hi:[1,0]
	v_pk_mul_f32 v[224:225], v[224:225], s[6:7] op_sel_hi:[1,0]
	s_waitcnt vmcnt(4)
	v_pk_mul_f32 v[230:231], v[230:231], s[6:7] op_sel_hi:[1,0]
	v_pk_mul_f32 v[228:229], v[228:229], s[6:7] op_sel_hi:[1,0]
	v_lshl_add_u64 v[232:233], v[106:107], 0, v[212:213]
	v_pk_fma_f32 v[112:113], v[80:81], v[180:181], v[100:101]
	v_pk_fma_f32 v[110:111], v[78:79], v[178:179], v[98:99]
	v_pk_fma_f32 v[108:109], v[76:77], v[176:177], v[104:105]
	v_pk_fma_f32 v[106:107], v[74:75], v[174:175], v[102:103]
	v_pk_fma_f32 v[104:105], v[72:73], v[172:173], v[226:227]
	v_pk_fma_f32 v[102:103], v[70:71], v[170:171], v[224:225]
	v_pk_fma_f32 v[100:101], v[68:69], v[168:169], v[230:231]
	v_pk_fma_f32 v[98:99], v[66:67], v[166:167], v[228:229]
	v_add_f32_e32 v78, 0, v202
	global_load_dwordx4 v[66:69], v[232:233], off
	global_load_dwordx4 v[70:73], v[232:233], off offset:16
	global_load_dwordx4 v[224:227], v[232:233], off offset:528
	global_load_dwordx4 v[228:231], v[232:233], off offset:512
	v_add_f32_e32 v79, 0, v206
	v_fma_f32 v80, v202, v206, 0
	v_mul_f32_e32 v232, v207, v207
	v_pk_mul_f32 v[74:75], v[196:197], v[200:201]
	v_pk_mul_f32 v[76:77], v[194:195], v[198:199]
	v_add_f32_e32 v75, v203, v78
	v_add_f32_e32 v76, v207, v79
	v_fmac_f32_e32 v232, v206, v206
	v_fmac_f32_e32 v80, v203, v207
	v_add_f32_e32 v75, v204, v75
	v_add_f32_e32 v76, v208, v76
	v_fmac_f32_e32 v232, v208, v208
	v_fmac_f32_e32 v80, v204, v208
	v_mov_b32_e32 v204, v194
	v_mov_b32_e32 v208, v198
	v_add_f32_e32 v75, v205, v75
	v_add_f32_e32 v76, v209, v76
	v_pk_mul_f32 v[78:79], v[204:205], v[208:209]
	v_add_f32_e32 v75, v194, v75
	v_add_f32_e32 v76, v198, v76
	v_add_f32_e32 v79, v79, v80
	v_fmac_f32_e32 v232, v209, v209
	v_add_f32_e32 v78, v78, v79
	v_add_f32_e32 v75, v195, v75
	v_add_f32_e32 v76, v199, v76
	v_fmac_f32_e32 v232, v198, v198
	v_add_f32_e32 v75, v196, v75
	v_add_f32_e32 v196, v200, v76
	v_add_f32_e32 v76, v77, v78
	v_fmac_f32_e32 v232, v199, v199
	v_add_f32_e32 v233, v74, v76
	v_fmac_f32_e32 v232, v200, v200
	v_add_f32_e32 v200, v197, v75
	v_fmac_f32_e32 v232, v201, v201
	v_fmac_f32_e32 v232, v190, v190
	v_fmac_f32_e32 v232, v191, v191
	v_fmac_f32_e32 v232, v192, v192
	v_fmac_f32_e32 v232, v193, v193
	v_fmac_f32_e32 v232, v182, v182
	v_fmac_f32_e32 v232, v183, v183
	v_fmac_f32_e32 v232, v184, v184
	v_fmac_f32_e32 v232, v185, v185
	s_waitcnt vmcnt(7)
	v_pk_mul_f32 v[76:77], v[82:83], s[6:7] op_sel_hi:[1,0]
	s_waitcnt vmcnt(5)
	v_pk_mul_f32 v[198:199], v[90:91], s[6:7] op_sel_hi:[1,0]
	s_waitcnt vmcnt(4)
	v_pk_mul_f32 v[82:83], v[96:97], s[6:7] op_sel_hi:[1,0]
	v_pk_mul_f32 v[74:75], v[84:85], s[6:7] op_sel_hi:[1,0]
	v_pk_mul_f32 v[78:79], v[88:89], s[6:7] op_sel_hi:[1,0]
	v_pk_mul_f32 v[84:85], v[94:95], s[6:7] op_sel_hi:[1,0]
	v_pk_mul_f32 v[194:195], v[92:93], s[6:7] op_sel_hi:[1,0]
	v_pk_fma_f32 v[88:89], v[56:57], v[172:173], v[82:83]
	v_pk_fma_f32 v[82:83], v[46:47], v[166:167], v[198:199]
	v_add_u32_e32 v46, 0xa0, v218
	v_pk_mul_f32 v[80:81], v[86:87], s[6:7] op_sel_hi:[1,0]
	v_pk_fma_f32 v[86:87], v[54:55], v[170:171], v[84:85]
	v_pk_fma_f32 v[84:85], v[48:49], v[168:169], v[194:195]
	v_ashrrev_i32_e32 v47, 31, v46
	v_add_u32_e32 v48, 0xfffff0a0, v218
	v_cmp_gt_i32_e32 vcc, s0, v46
	v_pk_fma_f32 v[96:97], v[64:65], v[180:181], v[74:75]
	v_pk_fma_f32 v[94:95], v[62:63], v[178:179], v[76:77]
	v_cndmask_b32_e32 v47, 0, v47, vcc
	v_cndmask_b32_e32 v46, v48, v46, vcc
	v_cndmask_b32_e32 v49, v219, v220, vcc
	v_cndmask_b32_e32 v48, v221, v222, vcc
	v_lshlrev_b64 v[46:47], 12, v[46:47]
	v_lshl_add_u64 v[46:47], v[48:49], 0, v[46:47]
	v_pk_fma_f32 v[92:93], v[60:61], v[176:177], v[78:79]
	v_pk_fma_f32 v[90:91], v[58:59], v[174:175], v[80:81]
	v_lshl_add_u64 v[58:59], v[46:47], 0, v[212:213]
	global_load_dwordx4 v[46:49], v[58:59], off offset:16
	global_load_dwordx4 v[54:57], v[58:59], off
	global_load_dwordx4 v[202:205], v[58:59], off offset:528
	global_load_dwordx4 v[206:209], v[58:59], off offset:512
	s_waitcnt vmcnt(7)
	v_pk_mul_f32 v[58:59], v[68:69], s[6:7] op_sel_hi:[1,0]
	v_pk_mul_f32 v[60:61], v[66:67], s[6:7] op_sel_hi:[1,0]
	v_pk_fma_f32 v[80:81], v[52:53], v[180:181], v[58:59]
	s_waitcnt vmcnt(6)
	v_pk_mul_f32 v[52:53], v[70:71], s[6:7] op_sel_hi:[1,0]
	v_pk_fma_f32 v[78:79], v[50:51], v[178:179], v[60:61]
	v_pk_mul_f32 v[50:51], v[72:73], s[6:7] op_sel_hi:[1,0]
	v_pk_fma_f32 v[74:75], v[42:43], v[174:175], v[52:53]
	s_waitcnt vmcnt(4)
	v_pk_mul_f32 v[42:43], v[230:231], s[6:7] op_sel_hi:[1,0]
	v_pk_fma_f32 v[76:77], v[44:45], v[176:177], v[50:51]
	v_pk_mul_f32 v[44:45], v[228:229], s[6:7] op_sel_hi:[1,0]
	v_pk_fma_f32 v[72:73], v[40:41], v[172:173], v[42:43]
	v_pk_mul_f32 v[40:41], v[224:225], s[6:7] op_sel_hi:[1,0]
	v_pk_fma_f32 v[70:71], v[38:39], v[170:171], v[44:45]
	v_pk_mul_f32 v[38:39], v[226:227], s[6:7] op_sel_hi:[1,0]
	v_pk_fma_f32 v[66:67], v[34:35], v[166:167], v[40:41]
	v_add_u32_e32 v34, 0xb0, v218
	v_pk_fma_f32 v[68:69], v[36:37], v[168:169], v[38:39]
	v_ashrrev_i32_e32 v35, 31, v34
	v_add_u32_e32 v36, 0xfffff0b0, v218
	v_cmp_gt_i32_e32 vcc, s0, v34
	v_add_f32_e32 v42, v201, v196
	v_add_f32_e32 v53, v190, v42
	v_cndmask_b32_e32 v35, 0, v35, vcc
	v_cndmask_b32_e32 v34, v36, v34, vcc
	v_cndmask_b32_e32 v37, v219, v220, vcc
	v_cndmask_b32_e32 v36, v221, v222, vcc
	v_lshlrev_b64 v[34:35], 12, v[34:35]
	v_lshl_add_u64 v[34:35], v[36:37], 0, v[34:35]
	v_lshl_add_u64 v[50:51], v[34:35], 0, v[212:213]
	global_load_dwordx4 v[34:37], v[50:51], off offset:16
	global_load_dwordx4 v[38:41], v[50:51], off
	global_load_dwordx4 v[42:45], v[50:51], off offset:528
	global_load_dwordx4 v[218:221], v[50:51], off offset:512
	v_add_f32_e32 v52, v186, v200
	v_mov_b32_e32 v196, v186
	v_mov_b32_e32 v200, v190
	v_pk_mul_f32 v[50:51], v[196:197], v[200:201]
	s_nop 0
	v_add_f32_e32 v51, v51, v233
	v_add_f32_e32 v58, v50, v51
	v_add_f32_e32 v50, v187, v52
	v_add_f32_e32 v51, v191, v53
	v_add_f32_e32 v59, v188, v50
	v_add_f32_e32 v60, v192, v51
	v_pk_mul_f32 v[50:51], v[188:189], v[192:193]
	v_pk_mul_f32 v[52:53], v[186:187], v[190:191]
	v_mov_b32_e32 v188, v162
	v_add_f32_e32 v51, v53, v58
	v_add_f32_e32 v52, v50, v51
	v_add_f32_e32 v50, v189, v59
	v_add_f32_e32 v51, v193, v60
	v_mov_b32_e32 v192, v182
	v_add_f32_e32 v53, v162, v50
	v_add_f32_e32 v58, v182, v51
	v_pk_mul_f32 v[50:51], v[188:189], v[192:193]
	v_mul_f32_e32 v186, v165, v185
	v_add_f32_e32 v51, v51, v52
	v_add_f32_e32 v59, v50, v51
	v_add_f32_e32 v50, v163, v53
	v_add_f32_e32 v51, v183, v58
	v_add_f32_e32 v187, v164, v50
	v_add_f32_e32 v58, v184, v51
	v_pk_mul_f32 v[50:51], v[164:165], v[184:185]
	v_pk_mul_f32 v[52:53], v[162:163], v[182:183]
	v_add_f32_e32 v162, v185, v58
	v_add_f32_e32 v51, v53, v59
	v_add_f32_e32 v164, v50, v51
	v_mbcnt_lo_u32_b32 v50, -1, 0
	v_mbcnt_hi_u32_b32 v163, -1, v50
	v_and_b32_e32 v50, 64, v163
	v_add_u32_e32 v182, 64, v50
	v_xor_b32_e32 v50, 1, v163
	v_cmp_lt_i32_e32 vcc, v50, v182
	s_waitcnt vmcnt(6)
	v_pk_mul_f32 v[52:53], v[54:55], s[6:7] op_sel_hi:[1,0]
	v_cndmask_b32_e32 v183, v163, v50, vcc
	v_pk_mul_f32 v[50:51], v[56:57], s[6:7] op_sel_hi:[1,0]
	v_pk_fma_f32 v[62:63], v[30:31], v[178:179], v[52:53]
	v_pk_fma_f32 v[64:65], v[32:33], v[180:181], v[50:51]
	v_pk_mul_f32 v[32:33], v[46:47], s[6:7] op_sel_hi:[1,0]
	v_pk_mul_f32 v[30:31], v[48:49], s[6:7] op_sel_hi:[1,0]
	v_pk_fma_f32 v[58:59], v[26:27], v[174:175], v[32:33]
	s_waitcnt vmcnt(4)
	v_pk_mul_f32 v[26:27], v[208:209], s[6:7] op_sel_hi:[1,0]
	v_pk_fma_f32 v[60:61], v[28:29], v[176:177], v[30:31]
	v_pk_mul_f32 v[28:29], v[206:207], s[6:7] op_sel_hi:[1,0]
	v_pk_fma_f32 v[56:57], v[16:17], v[172:173], v[26:27]
	v_pk_mul_f32 v[16:17], v[202:203], s[6:7] op_sel_hi:[1,0]
	v_pk_fma_f32 v[54:55], v[14:15], v[170:171], v[28:29]
	v_pk_mul_f32 v[14:15], v[204:205], s[6:7] op_sel_hi:[1,0]
	v_pk_fma_f32 v[50:51], v[10:11], v[166:167], v[16:17]
	v_pk_fma_f32 v[52:53], v[12:13], v[168:169], v[14:15]
	v_pk_mul_f32 v[204:205], v[146:147], v[146:147]
	s_waitcnt vmcnt(2)
	v_pk_mul_f32 v[10:11], v[40:41], s[6:7] op_sel_hi:[1,0]
	v_pk_mul_f32 v[12:13], v[38:39], s[6:7] op_sel_hi:[1,0]
	v_pk_fma_f32 v[16:17], v[24:25], v[180:181], v[10:11]
	v_pk_mul_f32 v[10:11], v[36:37], s[6:7] op_sel_hi:[1,0]
	v_pk_fma_f32 v[14:15], v[22:23], v[178:179], v[12:13]
	v_pk_mul_f32 v[22:23], v[34:35], s[6:7] op_sel_hi:[1,0]
	v_pk_fma_f32 v[12:13], v[20:21], v[176:177], v[10:11]
	s_waitcnt vmcnt(0)
	v_pk_mul_f32 v[20:21], v[218:219], s[6:7] op_sel_hi:[1,0]
	v_pk_fma_f32 v[10:11], v[18:19], v[174:175], v[22:23]
	v_pk_mul_f32 v[18:19], v[220:221], s[6:7] op_sel_hi:[1,0]
	v_pk_fma_f32 v[6:7], v[6:7], v[170:171], v[20:21]
	v_pk_mul_f32 v[20:21], v[42:43], s[6:7] op_sel_hi:[1,0]
	v_pk_fma_f32 v[8:9], v[8:9], v[172:173], v[18:19]
	v_pk_mul_f32 v[18:19], v[44:45], s[6:7] op_sel_hi:[1,0]
	v_pk_fma_f32 v[2:3], v[2:3], v[166:167], v[20:21]
	v_lshlrev_b32_e32 v20, 2, v183
	v_pk_fma_f32 v[4:5], v[4:5], v[168:169], v[18:19]
	ds_bpermute_b32 v19, v20, v223
	v_xor_b32_e32 v18, 2, v163
	v_cmp_lt_i32_e32 vcc, v18, v182
	ds_bpermute_b32 v31, v20, v162
	ds_bpermute_b32 v33, v20, v232
	v_cndmask_b32_e32 v18, v163, v18, vcc
	v_lshlrev_b32_e32 v24, 2, v18
	s_waitcnt lgkmcnt(2)
	v_add_f32_e32 v19, v223, v19
	ds_bpermute_b32 v21, v24, v19
	v_xor_b32_e32 v18, 4, v163
	v_cmp_lt_i32_e32 vcc, v18, v182
	s_waitcnt lgkmcnt(2)
	v_add_f32_e32 v31, v162, v31
	ds_bpermute_b32 v32, v24, v31
	v_cndmask_b32_e32 v18, v163, v18, vcc
	v_lshlrev_b32_e32 v25, 2, v18
	s_waitcnt lgkmcnt(1)
	v_add_f32_e32 v19, v19, v21
	ds_bpermute_b32 v21, v25, v19
	v_xor_b32_e32 v18, 8, v163
	v_cmp_lt_i32_e32 vcc, v18, v182
	s_waitcnt lgkmcnt(1)
	v_add_f32_e32 v31, v31, v32
	v_add_f32_e32 v33, v232, v33
	v_cndmask_b32_e32 v18, v163, v18, vcc
	v_lshlrev_b32_e32 v30, 2, v18
	s_waitcnt lgkmcnt(0)
	v_add_f32_e32 v19, v19, v21
	ds_bpermute_b32 v21, v30, v19
	v_xor_b32_e32 v18, 16, v163
	v_cmp_lt_i32_e32 vcc, v18, v182
	ds_bpermute_b32 v32, v25, v31
	ds_bpermute_b32 v36, v24, v33
	v_cndmask_b32_e32 v18, v163, v18, vcc
	v_lshlrev_b32_e32 v225, 2, v18
	s_waitcnt lgkmcnt(2)
	v_add_f32_e32 v19, v19, v21
	ds_bpermute_b32 v21, v225, v19
	v_xor_b32_e32 v18, 32, v163
	v_cmp_lt_i32_e32 vcc, v18, v182
	v_lshl_add_u64 v[22:23], s[20:21], 0, v[212:213]
	s_waitcnt lgkmcnt(0)
	v_add_f32_e32 v220, v19, v21
	v_cndmask_b32_e32 v18, v163, v18, vcc
	v_lshlrev_b32_e32 v224, 2, v18
	v_pk_add_f32 v[18:19], v[164:165], v[186:187]
	ds_bpermute_b32 v21, v20, v19
	ds_bpermute_b32 v20, v20, v18
	global_load_dwordx4 v[26:29], v[22:23], off offset:16
	global_load_dwordx4 v[38:41], v[22:23], off
	v_lshl_add_u64 v[34:35], s[22:23], 0, v[212:213]
	global_load_dwordx4 v[42:45], v[34:35], off offset:16
	global_load_dwordx4 v[46:49], v[34:35], off
	v_mul_f32_e32 v169, v159, v159
	s_waitcnt lgkmcnt(0)
	v_pk_add_f32 v[18:19], v[18:19], v[20:21]
	ds_bpermute_b32 v21, v24, v19
	ds_bpermute_b32 v20, v24, v18
	v_add_f32_e32 v24, v31, v32
	v_add_f32_e32 v32, v33, v36
	ds_bpermute_b32 v31, v30, v24
	ds_bpermute_b32 v33, v25, v32
	s_waitcnt lgkmcnt(2)
	v_pk_add_f32 v[18:19], v[18:19], v[20:21]
	ds_bpermute_b32 v21, v25, v19
	ds_bpermute_b32 v20, v25, v18
	s_waitcnt lgkmcnt(3)
	v_add_f32_e32 v24, v24, v31
	s_waitcnt lgkmcnt(2)
	v_add_f32_e32 v31, v32, v33
	ds_bpermute_b32 v32, v30, v31
	ds_bpermute_b32 v25, v225, v24
	s_waitcnt lgkmcnt(2)
	v_pk_add_f32 v[18:19], v[18:19], v[20:21]
	ds_bpermute_b32 v21, v30, v19
	ds_bpermute_b32 v20, v30, v18
	s_waitcnt lgkmcnt(3)
	v_add_f32_e32 v30, v31, v32
	ds_bpermute_b32 v31, v225, v30
	s_waitcnt lgkmcnt(3)
	v_add_f32_e32 v218, v24, v25
	v_fmac_f32_e32 v169, v158, v158
	s_waitcnt lgkmcnt(1)
	v_pk_add_f32 v[24:25], v[18:19], v[20:21]
	ds_bpermute_b32 v37, v225, v25
	s_waitcnt lgkmcnt(1)
	v_add_f32_e32 v222, v30, v31
	global_load_dwordx4 v[18:21], v[22:23], off offset:528
	global_load_dwordx4 v[30:33], v[22:23], off offset:512
	ds_bpermute_b32 v36, v225, v24
	v_mov_b32_e32 v166, v154
	v_mov_b32_e32 v167, v161
	v_add_f32_e32 v163, 0, v158
	v_fmac_f32_e32 v169, v160, v160
	s_waitcnt lgkmcnt(0)
	v_pk_add_f32 v[182:183], v[24:25], v[36:37]
	global_load_dwordx4 v[22:25], v[34:35], off offset:528
	s_nop 0
	global_load_dwordx4 v[34:37], v[34:35], off offset:512
	v_pk_mul_f32 v[164:165], v[166:167], v[166:167]
	v_add_f32_e32 v163, v159, v163
	v_add_f32_e32 v165, v165, v169
	v_add_f32_e32 v163, v160, v163
	v_add_f32_e32 v173, v164, v165
	v_add_f32_e32 v163, v161, v163
	v_add_f32_e32 v163, v154, v163
	v_add_f32_e32 v163, v155, v163
	v_add_f32_e32 v186, v156, v163
	v_mov_b32_e32 v187, v157
	ds_bpermute_b32 v221, v224, v220
	ds_bpermute_b32 v219, v224, v218
	ds_bpermute_b32 v223, v224, v222
	ds_bpermute_b32 v185, v224, v183
	ds_bpermute_b32 v184, v224, v182
	v_cmp_gt_u32_e32 vcc, 16, v217
	s_waitcnt vmcnt(7)
	v_mov_b32_e32 v164, v26
	s_waitcnt vmcnt(6)
	v_fma_f32 v168, v158, v38, 0
	v_mul_f32_e32 v170, v159, v39
	v_mul_f32_e32 v162, v158, v38
	v_fmac_f32_e32 v168, v159, v39
	v_mul_f32_e32 v171, v170, v170
	v_mov_b32_e32 v165, v41
	v_fmac_f32_e32 v171, v162, v162
	v_mul_f32_e32 v172, v160, v40
	v_fmac_f32_e32 v168, v160, v40
	v_pk_mul_f32 v[176:177], v[166:167], v[164:165]
	v_fmac_f32_e32 v171, v172, v172
	v_add_f32_e32 v168, v177, v168
	v_pk_mul_f32 v[166:167], v[176:177], v[176:177]
	v_pk_mul_f32 v[180:181], v[156:157], v[28:29]
	v_add_f32_e32 v167, v167, v171
	v_add_f32_e32 v171, v176, v168
	v_pk_mul_f32 v[168:169], v[154:155], v[154:155]
	v_add_f32_e32 v174, v166, v167
	v_pk_mul_f32 v[166:167], v[156:157], v[156:157]
	v_add_f32_e32 v163, v169, v173
	v_pk_mul_f32 v[178:179], v[154:155], v[26:27]
	v_add_f32_e32 v190, v166, v163
	v_pk_mul_f32 v[166:167], v[180:181], v[180:181]
	v_pk_mul_f32 v[168:169], v[178:179], v[178:179]
	v_add_f32_e32 v163, v179, v171
	v_add_f32_e32 v167, v169, v174
	v_add_f32_e32 v193, v166, v167
	s_waitcnt vmcnt(4)
	v_mov_b32_e32 v166, v46
	v_mov_b32_e32 v167, v38
	v_add_f32_e32 v192, v180, v163
	v_pk_fma_f32 v[162:163], v[162:163], v[166:167], 0 op_sel_hi:[0,1,0]
	v_mov_b32_e32 v168, v47
	v_mov_b32_e32 v169, v39
	v_pk_fma_f32 v[162:163], v[170:171], v[168:169], v[162:163] op_sel_hi:[0,1,1]
	v_mov_b32_e32 v170, v48
	v_mov_b32_e32 v171, v40
	v_pk_fma_f32 v[162:163], v[172:173], v[170:171], v[162:163] op_sel_hi:[0,1,1]
	v_mov_b32_e32 v172, v49
	v_mov_b32_e32 v173, v41
	v_pk_fma_f32 v[162:163], v[176:177], v[172:173], v[162:163] op_sel:[1,0,0]
	v_mov_b32_e32 v174, v42
	v_mov_b32_e32 v175, v26
	v_pk_fma_f32 v[162:163], v[176:177], v[174:175], v[162:163] op_sel_hi:[0,1,1]
	v_mov_b32_e32 v176, v43
	v_mov_b32_e32 v177, v27
	v_pk_fma_f32 v[162:163], v[178:179], v[176:177], v[162:163] op_sel:[1,0,0]
	v_mov_b32_e32 v178, v44
	v_mov_b32_e32 v179, v28
	v_pk_fma_f32 v[188:189], v[180:181], v[178:179], v[162:163] op_sel_hi:[0,1,1]
	v_add_f32_e32 v180, v157, v186
	v_mov_b32_e32 v186, v150
	v_add_f32_e32 v194, v150, v180
	v_pk_mul_f32 v[180:181], v[186:187], v[186:187]
	s_waitcnt vmcnt(3)
	v_pk_mul_f32 v[208:209], v[148:149], v[20:21]
	v_add_f32_e32 v181, v181, v190
	v_add_f32_e32 v195, v180, v181
	s_waitcnt vmcnt(2)
	v_mov_b32_e32 v180, v30
	v_mov_b32_e32 v181, v29
	v_pk_mul_f32 v[190:191], v[186:187], v[180:181]
	v_pk_mul_f32 v[212:213], v[208:209], v[208:209]
	v_pk_mul_f32 v[186:187], v[190:191], v[190:191]
	v_add_f32_e32 v192, v191, v192
	v_add_f32_e32 v187, v187, v193
	v_add_f32_e32 v198, v186, v187
	v_add_f32_e32 v186, v151, v194
	v_add_f32_e32 v196, v190, v192
	v_add_f32_e32 v199, v152, v186
	v_pk_mul_f32 v[186:187], v[152:153], v[152:153]
	v_pk_mul_f32 v[192:193], v[150:151], v[150:151]
	v_mov_b32_e32 v162, v45
	v_add_f32_e32 v187, v193, v195
	v_pk_mul_f32 v[194:195], v[152:153], v[32:33]
	v_pk_mul_f32 v[192:193], v[150:151], v[30:31]
	v_add_f32_e32 v200, v186, v187
	v_add_f32_e32 v201, v193, v196
	v_pk_mul_f32 v[186:187], v[194:195], v[194:195]
	v_pk_mul_f32 v[196:197], v[192:193], v[192:193]
	v_add_f32_e32 v201, v194, v201
	v_add_f32_e32 v187, v197, v198
	v_add_f32_e32 v202, v186, v187
	v_add_f32_e32 v186, v153, v199
	v_mov_b32_e32 v196, v146
	v_mov_b32_e32 v197, v153
	v_add_f32_e32 v203, v146, v186
	v_pk_mul_f32 v[186:187], v[196:197], v[196:197]
	v_mov_b32_e32 v163, v29
	v_add_f32_e32 v187, v187, v200
	v_add_f32_e32 v206, v186, v187
	v_mov_b32_e32 v186, v18
	v_mov_b32_e32 v187, v33
	v_pk_mul_f32 v[198:199], v[196:197], v[186:187]
	v_add_f32_e32 v200, v147, v203
	v_add_f32_e32 v207, v199, v201
	v_pk_mul_f32 v[196:197], v[198:199], v[198:199]
	v_add_f32_e32 v201, v205, v206
	v_add_f32_e32 v197, v197, v202
	v_add_f32_e32 v204, v198, v207
	v_mul_f32_e32 v207, v147, v19
	v_mov_b32_e32 v206, v208
	v_add_f32_e32 v205, v196, v197
	v_pk_mul_f32 v[196:197], v[206:207], v[206:207]
	v_fmac_f32_e32 v204, v147, v19
	v_add_f32_e32 v197, v197, v205
	v_mov_b32_e32 v205, v209
	v_pk_fma_f32 v[204:205], v[148:149], v[20:21], v[204:205]
	v_add_f32_e32 v197, v196, v197
	v_mov_b32_e32 v205, v213
	v_mov_b32_e32 v196, v209
	v_pk_add_f32 v[204:205], v[204:205], v[196:197]
	v_pk_fma_f32 v[196:197], v[190:191], v[162:163], v[188:189] op_sel:[1,0,0]
	s_waitcnt vmcnt(0)
	v_mov_b32_e32 v188, v34
	v_mov_b32_e32 v189, v30
	v_pk_fma_f32 v[196:197], v[190:191], v[188:189], v[196:197] op_sel_hi:[0,1,1]
	v_mov_b32_e32 v190, v35
	v_mov_b32_e32 v191, v31
	v_pk_fma_f32 v[196:197], v[192:193], v[190:191], v[196:197] op_sel:[1,0,0]
	v_mov_b32_e32 v192, v36
	v_mov_b32_e32 v193, v32
	v_pk_fma_f32 v[196:197], v[194:195], v[192:193], v[196:197] op_sel_hi:[0,1,1]
	v_mov_b32_e32 v194, v37
	v_mov_b32_e32 v195, v33
	v_pk_fma_f32 v[226:227], v[198:199], v[194:195], v[196:197] op_sel:[1,0,0]
	v_mov_b32_e32 v196, v22
	v_mov_b32_e32 v197, v18
	v_pk_fma_f32 v[226:227], v[198:199], v[196:197], v[226:227] op_sel_hi:[0,1,1]
	v_mov_b32_e32 v206, v207
	v_mov_b32_e32 v198, v23
	v_mov_b32_e32 v199, v19
	v_pk_mul_f32 v[202:203], v[148:149], v[148:149]
	v_pk_fma_f32 v[206:207], v[206:207], v[198:199], v[226:227] op_sel_hi:[0,1,1]
	v_mov_b32_e32 v226, v208
	v_mov_b32_e32 v227, v20
	v_mov_b32_e32 v228, v24
	v_mov_b32_e32 v229, v208
	v_add_f32_e32 v200, v148, v200
	v_add_f32_e32 v203, v202, v201
	v_mul_f32_e32 v201, v149, v149
	v_mov_b32_e32 v202, v149
	v_pk_fma_f32 v[206:207], v[226:227], v[228:229], v[206:207]
	v_mov_b32_e32 v226, v209
	v_mov_b32_e32 v227, v21
	v_mov_b32_e32 v208, v25
	v_pk_add_f32 v[200:201], v[202:203], v[200:201]
	v_pk_fma_f32 v[208:209], v[226:227], v[208:209], v[206:207]
	ds_bpermute_b32 v202, v225, v200
	ds_bpermute_b32 v203, v225, v201
	ds_bpermute_b32 v212, v225, v204
	ds_bpermute_b32 v213, v225, v205
	ds_bpermute_b32 v226, v225, v208
	ds_bpermute_b32 v227, v225, v209
	s_waitcnt lgkmcnt(4)
	v_pk_add_f32 v[200:201], v[200:201], v[202:203]
	ds_bpermute_b32 v202, v224, v200
	s_waitcnt lgkmcnt(3)
	v_pk_add_f32 v[206:207], v[204:205], v[212:213]
	ds_bpermute_b32 v203, v224, v201
	s_waitcnt lgkmcnt(2)
	v_pk_add_f32 v[204:205], v[208:209], v[226:227]
	ds_bpermute_b32 v212, v224, v206
	ds_bpermute_b32 v213, v224, v207
	ds_bpermute_b32 v208, v224, v204
	ds_bpermute_b32 v209, v224, v205
	s_and_saveexec_b64 s[4:5], vcc
	s_cbranch_execz .LBB0_458
	s_and_b32 s0, s3, 0x1fffff00
	v_or_b32_e32 v226, s0, v216
	v_or_b32_e32 v227, s35, v226
	v_mov_b32_e32 v226, 0
	v_mad_u64_u32 v[226:227], s[0:1], v227, 24, v[226:227]
	s_waitcnt lgkmcnt(4)
	v_pk_add_f32 v[200:201], v[200:201], v[202:203]
	s_waitcnt lgkmcnt(2)
	v_pk_add_f32 v[202:203], v[206:207], v[212:213]
	ds_write2_b64 v226, v[200:201], v[202:203] offset1:1
	s_waitcnt lgkmcnt(1)
	v_pk_add_f32 v[200:201], v[204:205], v[208:209]
	ds_write_b64 v226, v[200:201] offset:16

.LBB0_654:
	s_getpc_b64 s[100:101]
	v_lshlrev_b32_e32 v243, 7, v0
	v_min_u32_e32 v243, 0x2780, v243
	global_load_dword v243, v243, s[100:101]
	s_lshl_b32 s0, s7, 5
	s_lshl_b32 s1, s10, 8
	v_lshrrev_b32_e32 v122, 1, v0
	s_or_b32 s0, s1, s0
	v_and_or_b32 v122, v122, 24, s0
	s_mul_i32 s98, s6, 0xc0
	s_add_i32 s0, s98, 0xfffff000
	s_ashr_i32 s0, s0, 11
	s_add_i32 s0, s0, 1
	s_max_i32 s0, s0, 0
	s_mulk_i32 s0, 0x1800
	s_add_i32 s101, s98, 0xbf
	s_lshr_b32 s101, s101, 11
	s_lshl_b32 s101, s101, 11
	s_sub_i32 s101, s101, s98
	s_mov_b32 s100, 99
	s_cmp_lt_i32 s101, 1
	s_cbranch_scc1 .Lp9_nostraddle
	s_add_i32 s99, s98, s101
	s_cmp_lt_u32 s99, 0x1000
	s_cbranch_scc1 .Lp9_nostraddle
	s_cmp_eq_u32 s101, 64
	s_cselect_b32 s100, 4, 6
	s_cselect_b32 s99, 1, 4
	s_cmp_eq_u32 s40, 0
	s_cselect_b32 s100, s100, s99
